# v081 + ffn-input rows relocated into the same XCD's gate rows (GT + 12 MiB x): merge->out-proj boundary XCD-local too; 7 XCD-local barriers (t=0,4,5,6,8,12,13)
# speedup vs baseline: 1.0161x; 1.0027x over previous
;     __device__ __forceinline__ const float* in(int i) const { return *(const __attribute__((address_space(4))) cfptr_t*)(p + 8 * i); }
;     __device__ __forceinline__ float* out() const { return *(const __attribute__((address_space(4))) fptr_t*)(p + 256); }
;     __device__ __forceinline__ unsigned char* ws() const { return *(const __attribute__((address_space(4))) ucptr_t*)(p + 264); }
; __device__ __forceinline__ void run_phase(const KA& A, const Ctx& F, int ph) {
;     ...
;     for (int gi = 0; gi < ngemm; ++gi) {
;         pg8::Gemm g; pg8::EpiAny E; E.kind = 0; E.gi = gi; E.ws = F.ws; E.base = hin; E.out = F.out; E.gain = A.in(28) + l * D;
;         if (k == 0) { g = pg8::Gemm{XN, (const bf16*)(wl + WO_IN), NIN, D, D, D}; E.kind = 0; }
;         else if (k == 3) { g = pg8::Gemm{PS + C_SSM, (const bf16*)(wl + WO_GLU), 512, 256, PSW, 256}; E.kind = 4; }
;         else if (k == 5) { g = pg8::Gemm{XN, (const bf16*)(wl + WO_OUT), D, D, D, D}; E.kind = 2; E.gi = (2 * l) << 2; E.out = hmid; }
;         else if (k == 6) { g = pg8::Gemm{(const bf16*)(F.ws + WS_GT), (const bf16*)(wl + WO_GU), 2 * FFH, D, D, D}; E.kind = 3; }
;         else { g = pg8::Gemm{PS, (const bf16*)(wl + WO_DN), D, FFH, FFH, FFH}; E.kind = 2; E.base = hmid;
;                E.gi = ((2 * l + 1) << 2) | 1 | ((l == DEPTH - 1) ? 2 : 0); E.gain = (l == DEPTH - 1) ? A.in(31) : A.in(1) + (l + 1) * D; }
.LBB0_219:
	v_readlane_b32 s0, v253, 58
	v_readlane_b32 s1, v253, 59
	s_load_dwordx2 s[0:1], s[0:1], 0xe0
	s_lshl_b32 s10, s79, 10
	s_ashr_i32 s11, s10, 31
	s_lshl_b64 s[2:3], s[10:11], 2
	s_mov_b64 s[16:17], -1
	s_waitcnt lgkmcnt(0)
	s_add_u32 s2, s0, s2
	s_addc_u32 s3, s1, s3
	s_lshl_b32 s11, s79, 3
	s_mov_b64 s[12:13], 0
	s_cmp_lt_i32 s25, 5
	s_mov_b64 s[14:15], 0
	s_cbranch_scc1 .LBB0_226
	s_mov_b64 s[0:1], 0
	s_cmp_gt_i32 s25, 5
	s_cbranch_scc0 .LBB0_224
	s_cmp_eq_u32 s25, 6
	s_mov_b64 s[14:15], -1
	s_cbranch_scc0 .LBB0_223
	s_add_u32 s4, s84, 0x1000000
	v_readlane_b32 s16, v253, 60
	s_addc_u32 s5, s85, 0
	v_readlane_b32 s18, v253, 62
	v_readlane_b32 s17, v253, 61
	v_readlane_b32 s19, v253, 63
	s_add_u32 s8, s18, 0x13400000
	s_addc_u32 s9, s19, 0
	s_and_b32 s14, s80, 7
	s_lshl_b32 s14, s14, 22
	s_add_u32 s8, s8, s14
	s_addc_u32 s9, s9, 0
	s_mov_b64 s[14:15], 0
	s_mov_b64 s[6:7], s[16:17]

;     __device__ __forceinline__ void operator()(const f32x4 (&acc)[2][2][4][2], const Unit& u, int wr, int wc, int fr, int fq) const { epi_merge((bf16_t*)(ws + EP_XN), ws + EP_GT, acc, u, wr, wc, fr, fq); }
;     __device__ __forceinline__ const float* in(int i) const { return *(const __attribute__((address_space(4))) cfptr_t*)(p + 8 * i); }
;     __device__ __forceinline__ float* out() const { return *(const __attribute__((address_space(4))) fptr_t*)(p + 256); }
;     __device__ __forceinline__ unsigned char* ws() const { return *(const __attribute__((address_space(4))) ucptr_t*)(p + 264); }
;     __device__ __forceinline__ void operator()(const f32x4 (&acc)[2][2][4][2], const Unit& u, int wr, int wc, int fr, int fq) const {
;         if (kind == 0) epi_win((bf16_t*)(ws + EP_PS), ws + EP_GT, (bf16_t*)(ws + EP_BR), acc, u, wr, wc, fr, fq);
;         else if (kind == 2) epi_res_norm(out, (bf16_t*)(ws + ((gi & 1) ? EP_XN : EP_GT)), gain, (float*)(ws + EP_SSQ), (unsigned*)(ws + EP_CNT) + (gi >> 2) * 8192, (gi & 2) != 0, acc, u, wr, wc, fr, fq);
;         else if (kind == 3) epi_pair<0>((bf16_t*)(ws + EP_PS), 2816, acc, u, wr, wc, fr, fq);
;         else if (kind == 4) epi_pair<1>((bf16_t*)(ws + EP_PS) + 768, 2816, acc, u, wr, wc, fr, fq);
;     }
; __device__ __forceinline__ void run_phase(const KA& A, const Ctx& F, int ph) {
;     ...
;         else if (k == 5) { g = pg8::Gemm{XN, (const bf16*)(wl + WO_OUT), D, D, D, D}; E.kind = 2; E.gi = (2 * l) << 2; E.out = hmid; }
;         else if (k == 6) { g = pg8::Gemm{(const bf16*)(F.ws + WS_GT), (const bf16*)(wl + WO_GU), 2 * FFH, D, D, D}; E.kind = 3; }
;         else { g = pg8::Gemm{PS, (const bf16*)(wl + WO_DN), D, FFH, FFH, FFH}; E.kind = 2; E.base = hmid;
;                E.gi = ((2 * l + 1) << 2) | 1 | ((l == DEPTH - 1) ? 2 : 0); E.gain = (l == DEPTH - 1) ? A.in(31) : A.in(1) + (l + 1) * D; }
.LBB0_254:
	s_waitcnt vmcnt(6)
	s_barrier
	v_lshlrev_b32_e32 v130, 6, v244
	v_lshlrev_b32_e32 v131, 2, v244
	s_lshr_b32 s76, s16, 6
	v_and_or_b32 v130, v130, s77, v80
	s_lshl_b32 s14, s21, 13
	v_and_b32_e32 v131, 32, v131
	v_bitop3_b32 v130, v130, s14, v131 bitop3:0xde
	s_lshl_b32 s14, s34, 12
	v_lshlrev_b32_e32 v132, 2, v243
	s_add_i32 s77, s76, -2
	v_lshl_or_b32 v131, v243, 6, v80
	v_and_b32_e32 v132, 32, v132
	s_cmpk_lt_u32 s17, 0x100
	v_bitop3_b32 v245, v131, s14, v132 bitop3:0xde
	s_cselect_b64 s[14:15], -1, 0
	s_or_b32 s16, s34, s21
	s_cmp_eq_u32 s16, 0
	v_readlane_b32 s20, v253, 60
	s_cselect_b64 s[16:17], -1, 0
	s_sub_i32 s82, s19, s65
	v_readlane_b32 s22, v253, 62
	v_readlane_b32 s23, v253, 63
	s_lshl_b32 s79, s19, 2
	s_lshl_b32 s81, s19, 3
	s_lshl_b32 s83, s82, 4
	s_mov_b64 s[54:55], s[22:23]
	v_readlane_b32 s21, v253, 61
	s_add_u32 s20, s54, 0x8400600
	s_addc_u32 s21, s55, 0
	s_mul_i32 s91, s19, 12
	s_and_b32 s22, s80, 7
	s_lshl_b32 s22, s22, 22
	s_bitcmp0_b32 s18, 0
	s_mov_b32 s19, 0x13400000
	s_cselect_b32 s19, s19, 0x4400000
	s_cselect_b32 s22, s22, 0
	s_add_u32 s26, s54, s19
	s_addc_u32 s27, s55, 0
	s_add_u32 s26, s26, s22
	s_addc_u32 s27, s27, 0
	s_add_u32 s28, s54, 0x1fa00000
	s_addc_u32 s29, s55, 0
	s_lshl_b32 s19, s18, 11
	s_and_b32 s22, s19, 0xffffe000
	s_ashr_i32 s23, s22, 31
	s_lshl_b64 s[22:23], s[22:23], 2
	s_add_u32 s19, s54, s22
	s_addc_u32 s22, s55, s23
	s_add_u32 s84, s19, 0x10000
	s_addc_u32 s85, s22, 0
	s_and_b32 s19, s18, 2
	s_cmp_eq_u32 s19, 0
	s_cselect_b64 s[30:31], -1, 0
	s_cmp_lg_u32 s19, 0
	s_cselect_b64 s[36:37], -1, 0
	s_add_u32 s50, s54, 0x13400000
	v_lshl_add_u64 v[192:193], s[28:29], 0, v[80:81]
	s_addc_u32 s51, s55, 0
	v_add_u32_e32 v80, v146, v144
	v_or_b32_e32 v131, v143, v243
	s_add_u32 s52, s54, 0x1a500000
	v_add_lshl_u32 v80, v80, v145, 1
	s_waitcnt vmcnt(4)
	v_cmp_eq_u32_e64 s[44:45], 0, v131
	v_and_b32_e32 v131, 16, v142
	v_lshlrev_b32_e32 v132, 7, v143
	s_addc_u32 s53, s55, 0
	v_lshl_add_u64 v[194:195], s[0:1], 0, v[80:81]
	v_add_u32_e32 v80, v149, v147
	v_or3_b32 v131, v131, v132, s35
	s_cmp_lt_u32 s18, 4
	v_add_lshl_u32 v80, v80, v148, 1
	s_mov_b32 s78, 0
	v_cmp_eq_u32_e64 s[42:43], 0, v143
	v_or_b32_e32 v246, 0xfffff500, v131
	v_cmp_eq_u32_e64 s[46:47], 15, v243
	s_cselect_b64 s[54:55], -1, 0
	v_or_b32_e32 v247, s35, v142
	v_lshl_add_u64 v[196:197], s[0:1], 0, v[80:81]
	v_add_u32_e32 v248, 0, v130
	s_lshl_b32 s56, s34, 2
	s_barrier
	s_branch .LBB0_257

; __global__ void __launch_bounds__(NTHREADS, 2) mega_fwd(Args args) {
;     ...
;         if (ph + 1 < args.ph_hi) {
;     ...
;             for (int e_ = 0; e_ < EXTRA_SYNCS; ++e_) { XcdBarrier b2 = bar; asm volatile("" : "+s"(b2.bar)); int tb_; asm volatile("v_mbcnt_lo_u32_b32 %0, -1, 0\n\tv_mbcnt_hi_u32_b32 %0, -1, %0\n\tv_or_b32 %0, %1, %0" : "=&v"(tb_) : "s"(wv0 << 6)); xcd_barrier(b2, tb_); }
;     ...
;             if (args.ph_lo < 0) { __threadfence(); cg::this_grid().sync(); }
;             { XcdBarrier b2 = bar; asm volatile("" : "+s"(b2.bar)); int tb_; asm volatile("v_mbcnt_lo_u32_b32 %0, -1, 0\n\tv_mbcnt_hi_u32_b32 %0, -1, %0\n\tv_or_b32 %0, %1, %0" : "=&v"(tb_) : "s"(wv0 << 6)); xcd_barrier(b2, tb_); } }
.LBB0_552:
	s_andn2_saveexec_b64 s[4:5], s[4:5]
	s_cbranch_execz .LBB0_8
	s_add_i32 s4, s70, -2
	s_cmp_lt_u32 s4, 15
	s_cbranch_scc0 .Lxb_global
	s_lshr_b32 s5, 0x3171, s4
	s_and_b32 s5, s5, 1
	s_cbranch_scc0 .Lxb_global
	v_readfirstlane_b32 s5, v18
	s_cmp_eq_u32 s5, 0
	s_cbranch_scc0 .Lxb_global
	s_mov_b64 s[0:1], exec
	s_branch .LBB0_7
